# in-projection gelu epilogue blocks rewritten in place with packed f32 ops (same op order)
# speedup vs baseline: 1.0004x; 1.0004x over previous
.LBB0_102:
	s_andn2_b64 vcc, exec, s[4:5]
	s_cbranch_vccnz .LBB0_104
	s_mov_b32 s76, 0x3d372713
	s_mov_b32 s77, 0x3d372713
	s_mov_b32 s78, 0x3f4c422a
	s_mov_b32 s79, 0x3f4c422a
	s_mov_b32 s80, 0xc038aa3b
	s_mov_b32 s81, 0xc038aa3b
	s_mov_b32 s82, 1.0
	s_mov_b32 s83, 1.0
	v_pk_mul_f32 v[160:161], v[152:153], s[76:77]
	v_pk_mul_f32 v[164:165], v[148:149], s[76:77]
	v_pk_mul_f32 v[162:163], v[154:155], s[76:77]
	v_pk_mul_f32 v[166:167], v[150:151], s[76:77]
	v_pk_mul_f32 v[160:161], v[152:153], v[160:161]
	v_pk_mul_f32 v[164:165], v[148:149], v[164:165]
	v_pk_mul_f32 v[162:163], v[154:155], v[162:163]
	v_pk_mul_f32 v[166:167], v[150:151], v[166:167]
	v_pk_fma_f32 v[160:161], v[152:153], v[160:161], v[152:153]
	v_pk_fma_f32 v[164:165], v[148:149], v[164:165], v[148:149]
	v_pk_fma_f32 v[162:163], v[154:155], v[162:163], v[154:155]
	v_pk_fma_f32 v[166:167], v[150:151], v[166:167], v[150:151]
	v_pk_mul_f32 v[160:161], v[160:161], s[78:79]
	v_pk_mul_f32 v[164:165], v[164:165], s[78:79]
	v_pk_mul_f32 v[162:163], v[162:163], s[78:79]
	v_pk_mul_f32 v[166:167], v[166:167], s[78:79]
	v_pk_mul_f32 v[160:161], v[160:161], s[80:81]
	v_pk_mul_f32 v[164:165], v[164:165], s[80:81]
	v_pk_mul_f32 v[162:163], v[162:163], s[80:81]
	v_pk_mul_f32 v[166:167], v[166:167], s[80:81]
	v_exp_f32_e32 v160, v160
	v_exp_f32_e32 v161, v161
	v_exp_f32_e32 v164, v164
	v_exp_f32_e32 v165, v165
	v_exp_f32_e32 v162, v162
	v_exp_f32_e32 v163, v163
	v_exp_f32_e32 v166, v166
	v_exp_f32_e32 v167, v167
	s_nop 0
	v_pk_add_f32 v[160:161], v[160:161], s[82:83]
	v_pk_add_f32 v[164:165], v[164:165], s[82:83]
	v_pk_add_f32 v[162:163], v[162:163], s[82:83]
	v_pk_add_f32 v[166:167], v[166:167], s[82:83]
	v_rcp_f32_e32 v160, v160
	v_rcp_f32_e32 v161, v161
	v_rcp_f32_e32 v164, v164
	v_rcp_f32_e32 v165, v165
	v_rcp_f32_e32 v162, v162
	v_rcp_f32_e32 v163, v163
	v_rcp_f32_e32 v166, v166
	v_rcp_f32_e32 v167, v167
	s_nop 0
	v_pk_mul_f32 v[160:161], v[152:153], v[160:161]
	v_pk_mul_f32 v[164:165], v[148:149], v[164:165]
	v_pk_mul_f32 v[162:163], v[154:155], v[162:163]
	v_pk_mul_f32 v[166:167], v[150:151], v[166:167]

.LBB0_108:
	s_andn2_b64 vcc, exec, s[4:5]
	s_cbranch_vccnz .LBB0_110
	s_mov_b32 s76, 0x3d372713
	s_mov_b32 s77, 0x3d372713
	s_mov_b32 s78, 0x3f4c422a
	s_mov_b32 s79, 0x3f4c422a
	s_mov_b32 s80, 0xc038aa3b
	s_mov_b32 s81, 0xc038aa3b
	s_mov_b32 s82, 1.0
	s_mov_b32 s83, 1.0
	v_pk_mul_f32 v[148:149], v[144:145], s[76:77]
	v_pk_mul_f32 v[152:153], v[140:141], s[76:77]
	v_pk_mul_f32 v[150:151], v[146:147], s[76:77]
	v_pk_mul_f32 v[154:155], v[142:143], s[76:77]
	v_pk_mul_f32 v[148:149], v[144:145], v[148:149]
	v_pk_mul_f32 v[152:153], v[140:141], v[152:153]
	v_pk_mul_f32 v[150:151], v[146:147], v[150:151]
	v_pk_mul_f32 v[154:155], v[142:143], v[154:155]
	v_pk_fma_f32 v[148:149], v[144:145], v[148:149], v[144:145]
	v_pk_fma_f32 v[152:153], v[140:141], v[152:153], v[140:141]
	v_pk_fma_f32 v[150:151], v[146:147], v[150:151], v[146:147]
	v_pk_fma_f32 v[154:155], v[142:143], v[154:155], v[142:143]
	v_pk_mul_f32 v[148:149], v[148:149], s[78:79]
	v_pk_mul_f32 v[152:153], v[152:153], s[78:79]
	v_pk_mul_f32 v[150:151], v[150:151], s[78:79]
	v_pk_mul_f32 v[154:155], v[154:155], s[78:79]
	v_pk_mul_f32 v[148:149], v[148:149], s[80:81]
	v_pk_mul_f32 v[152:153], v[152:153], s[80:81]
	v_pk_mul_f32 v[150:151], v[150:151], s[80:81]
	v_pk_mul_f32 v[154:155], v[154:155], s[80:81]
	v_exp_f32_e32 v148, v148
	v_exp_f32_e32 v149, v149
	v_exp_f32_e32 v152, v152
	v_exp_f32_e32 v153, v153
	v_exp_f32_e32 v150, v150
	v_exp_f32_e32 v151, v151
	v_exp_f32_e32 v154, v154
	v_exp_f32_e32 v155, v155
	s_nop 0
	v_pk_add_f32 v[148:149], v[148:149], s[82:83]
	v_pk_add_f32 v[152:153], v[152:153], s[82:83]
	v_pk_add_f32 v[150:151], v[150:151], s[82:83]
	v_pk_add_f32 v[154:155], v[154:155], s[82:83]
	v_rcp_f32_e32 v148, v148
	v_rcp_f32_e32 v149, v149
	v_rcp_f32_e32 v152, v152
	v_rcp_f32_e32 v153, v153
	v_rcp_f32_e32 v150, v150
	v_rcp_f32_e32 v151, v151
	v_rcp_f32_e32 v154, v154
	v_rcp_f32_e32 v155, v155
	s_nop 0
	v_pk_mul_f32 v[148:149], v[144:145], v[148:149]
	v_pk_mul_f32 v[152:153], v[140:141], v[152:153]
	v_pk_mul_f32 v[150:151], v[146:147], v[150:151]
	v_pk_mul_f32 v[154:155], v[142:143], v[154:155]

.LBB0_114:
	s_andn2_b64 vcc, exec, s[4:5]
	s_cbranch_vccnz .LBB0_116
	s_mov_b32 s76, 0x3d372713
	s_mov_b32 s77, 0x3d372713
	s_mov_b32 s78, 0x3f4c422a
	s_mov_b32 s79, 0x3f4c422a
	s_mov_b32 s80, 0xc038aa3b
	s_mov_b32 s81, 0xc038aa3b
	s_mov_b32 s82, 1.0
	s_mov_b32 s83, 1.0
	v_pk_mul_f32 v[140:141], v[132:133], s[76:77]
	v_pk_mul_f32 v[144:145], v[128:129], s[76:77]
	v_pk_mul_f32 v[142:143], v[134:135], s[76:77]
	v_pk_mul_f32 v[146:147], v[130:131], s[76:77]
	v_pk_mul_f32 v[140:141], v[132:133], v[140:141]
	v_pk_mul_f32 v[144:145], v[128:129], v[144:145]
	v_pk_mul_f32 v[142:143], v[134:135], v[142:143]
	v_pk_mul_f32 v[146:147], v[130:131], v[146:147]
	v_pk_fma_f32 v[140:141], v[132:133], v[140:141], v[132:133]
	v_pk_fma_f32 v[144:145], v[128:129], v[144:145], v[128:129]
	v_pk_fma_f32 v[142:143], v[134:135], v[142:143], v[134:135]
	v_pk_fma_f32 v[146:147], v[130:131], v[146:147], v[130:131]
	v_pk_mul_f32 v[140:141], v[140:141], s[78:79]
	v_pk_mul_f32 v[144:145], v[144:145], s[78:79]
	v_pk_mul_f32 v[142:143], v[142:143], s[78:79]
	v_pk_mul_f32 v[146:147], v[146:147], s[78:79]
	v_pk_mul_f32 v[140:141], v[140:141], s[80:81]
	v_pk_mul_f32 v[144:145], v[144:145], s[80:81]
	v_pk_mul_f32 v[142:143], v[142:143], s[80:81]
	v_pk_mul_f32 v[146:147], v[146:147], s[80:81]
	v_exp_f32_e32 v140, v140
	v_exp_f32_e32 v141, v141
	v_exp_f32_e32 v144, v144
	v_exp_f32_e32 v145, v145
	v_exp_f32_e32 v142, v142
	v_exp_f32_e32 v143, v143
	v_exp_f32_e32 v146, v146
	v_exp_f32_e32 v147, v147
	s_nop 0
	v_pk_add_f32 v[140:141], v[140:141], s[82:83]
	v_pk_add_f32 v[144:145], v[144:145], s[82:83]
	v_pk_add_f32 v[142:143], v[142:143], s[82:83]
	v_pk_add_f32 v[146:147], v[146:147], s[82:83]
	v_rcp_f32_e32 v140, v140
	v_rcp_f32_e32 v141, v141
	v_rcp_f32_e32 v144, v144
	v_rcp_f32_e32 v145, v145
	v_rcp_f32_e32 v142, v142
	v_rcp_f32_e32 v143, v143
	v_rcp_f32_e32 v146, v146
	v_rcp_f32_e32 v147, v147
	s_nop 0
	v_pk_mul_f32 v[140:141], v[132:133], v[140:141]
	v_pk_mul_f32 v[144:145], v[128:129], v[144:145]
	v_pk_mul_f32 v[142:143], v[134:135], v[142:143]
	v_pk_mul_f32 v[146:147], v[130:131], v[146:147]

.LBB0_120:
	s_andn2_b64 vcc, exec, s[4:5]
	s_cbranch_vccnz .LBB0_122
	s_mov_b32 s76, 0x3d372713
	s_mov_b32 s77, 0x3d372713
	s_mov_b32 s78, 0x3f4c422a
	s_mov_b32 s79, 0x3f4c422a
	s_mov_b32 s80, 0xc038aa3b
	s_mov_b32 s81, 0xc038aa3b
	s_mov_b32 s82, 1.0
	s_mov_b32 s83, 1.0
	v_pk_mul_f32 v[128:129], v[124:125], s[76:77]
	v_pk_mul_f32 v[132:133], v[120:121], s[76:77]
	v_pk_mul_f32 v[130:131], v[126:127], s[76:77]
	v_pk_mul_f32 v[134:135], v[122:123], s[76:77]
	v_pk_mul_f32 v[128:129], v[124:125], v[128:129]
	v_pk_mul_f32 v[132:133], v[120:121], v[132:133]
	v_pk_mul_f32 v[130:131], v[126:127], v[130:131]
	v_pk_mul_f32 v[134:135], v[122:123], v[134:135]
	v_pk_fma_f32 v[128:129], v[124:125], v[128:129], v[124:125]
	v_pk_fma_f32 v[132:133], v[120:121], v[132:133], v[120:121]
	v_pk_fma_f32 v[130:131], v[126:127], v[130:131], v[126:127]
	v_pk_fma_f32 v[134:135], v[122:123], v[134:135], v[122:123]
	v_pk_mul_f32 v[128:129], v[128:129], s[78:79]
	v_pk_mul_f32 v[132:133], v[132:133], s[78:79]
	v_pk_mul_f32 v[130:131], v[130:131], s[78:79]
	v_pk_mul_f32 v[134:135], v[134:135], s[78:79]
	v_pk_mul_f32 v[128:129], v[128:129], s[80:81]
	v_pk_mul_f32 v[132:133], v[132:133], s[80:81]
	v_pk_mul_f32 v[130:131], v[130:131], s[80:81]
	v_pk_mul_f32 v[134:135], v[134:135], s[80:81]
	v_exp_f32_e32 v128, v128
	v_exp_f32_e32 v129, v129
	v_exp_f32_e32 v132, v132
	v_exp_f32_e32 v133, v133
	v_exp_f32_e32 v130, v130
	v_exp_f32_e32 v131, v131
	v_exp_f32_e32 v134, v134
	v_exp_f32_e32 v135, v135
	s_nop 0
	v_pk_add_f32 v[128:129], v[128:129], s[82:83]
	v_pk_add_f32 v[132:133], v[132:133], s[82:83]
	v_pk_add_f32 v[130:131], v[130:131], s[82:83]
	v_pk_add_f32 v[134:135], v[134:135], s[82:83]
	v_rcp_f32_e32 v128, v128
	v_rcp_f32_e32 v129, v129
	v_rcp_f32_e32 v132, v132
	v_rcp_f32_e32 v133, v133
	v_rcp_f32_e32 v130, v130
	v_rcp_f32_e32 v131, v131
	v_rcp_f32_e32 v134, v134
	v_rcp_f32_e32 v135, v135
	s_nop 0
	v_pk_mul_f32 v[128:129], v[124:125], v[128:129]
	v_pk_mul_f32 v[132:133], v[120:121], v[132:133]
	v_pk_mul_f32 v[130:131], v[126:127], v[130:131]
	v_pk_mul_f32 v[134:135], v[122:123], v[134:135]

.LBB0_126:
	s_andn2_b64 vcc, exec, s[4:5]
	s_cbranch_vccnz .LBB0_128
	s_mov_b32 s76, 0x3d372713
	s_mov_b32 s77, 0x3d372713
	s_mov_b32 s78, 0x3f4c422a
	s_mov_b32 s79, 0x3f4c422a
	s_mov_b32 s80, 0xc038aa3b
	s_mov_b32 s81, 0xc038aa3b
	s_mov_b32 s82, 1.0
	s_mov_b32 s83, 1.0
	v_pk_mul_f32 v[120:121], v[112:113], s[76:77]
	v_pk_mul_f32 v[124:125], v[108:109], s[76:77]
	v_pk_mul_f32 v[122:123], v[114:115], s[76:77]
	v_pk_mul_f32 v[126:127], v[110:111], s[76:77]
	v_pk_mul_f32 v[120:121], v[112:113], v[120:121]
	v_pk_mul_f32 v[124:125], v[108:109], v[124:125]
	v_pk_mul_f32 v[122:123], v[114:115], v[122:123]
	v_pk_mul_f32 v[126:127], v[110:111], v[126:127]
	v_pk_fma_f32 v[120:121], v[112:113], v[120:121], v[112:113]
	v_pk_fma_f32 v[124:125], v[108:109], v[124:125], v[108:109]
	v_pk_fma_f32 v[122:123], v[114:115], v[122:123], v[114:115]
	v_pk_fma_f32 v[126:127], v[110:111], v[126:127], v[110:111]
	v_pk_mul_f32 v[120:121], v[120:121], s[78:79]
	v_pk_mul_f32 v[124:125], v[124:125], s[78:79]
	v_pk_mul_f32 v[122:123], v[122:123], s[78:79]
	v_pk_mul_f32 v[126:127], v[126:127], s[78:79]
	v_pk_mul_f32 v[120:121], v[120:121], s[80:81]
	v_pk_mul_f32 v[124:125], v[124:125], s[80:81]
	v_pk_mul_f32 v[122:123], v[122:123], s[80:81]
	v_pk_mul_f32 v[126:127], v[126:127], s[80:81]
	v_exp_f32_e32 v120, v120
	v_exp_f32_e32 v121, v121
	v_exp_f32_e32 v124, v124
	v_exp_f32_e32 v125, v125
	v_exp_f32_e32 v122, v122
	v_exp_f32_e32 v123, v123
	v_exp_f32_e32 v126, v126
	v_exp_f32_e32 v127, v127
	s_nop 0
	v_pk_add_f32 v[120:121], v[120:121], s[82:83]
	v_pk_add_f32 v[124:125], v[124:125], s[82:83]
	v_pk_add_f32 v[122:123], v[122:123], s[82:83]
	v_pk_add_f32 v[126:127], v[126:127], s[82:83]
	v_rcp_f32_e32 v120, v120
	v_rcp_f32_e32 v121, v121
	v_rcp_f32_e32 v124, v124
	v_rcp_f32_e32 v125, v125
	v_rcp_f32_e32 v122, v122
	v_rcp_f32_e32 v123, v123
	v_rcp_f32_e32 v126, v126
	v_rcp_f32_e32 v127, v127
	s_nop 0
	v_pk_mul_f32 v[120:121], v[112:113], v[120:121]
	v_pk_mul_f32 v[124:125], v[108:109], v[124:125]
	v_pk_mul_f32 v[122:123], v[114:115], v[122:123]
	v_pk_mul_f32 v[126:127], v[110:111], v[126:127]

.LBB0_132:
	s_andn2_b64 vcc, exec, s[4:5]
	s_cbranch_vccnz .LBB0_134
	s_mov_b32 s76, 0x3d372713
	s_mov_b32 s77, 0x3d372713
	s_mov_b32 s78, 0x3f4c422a
	s_mov_b32 s79, 0x3f4c422a
	s_mov_b32 s80, 0xc038aa3b
	s_mov_b32 s81, 0xc038aa3b
	s_mov_b32 s82, 1.0
	s_mov_b32 s83, 1.0
	v_pk_mul_f32 v[108:109], v[104:105], s[76:77]
	v_pk_mul_f32 v[112:113], v[100:101], s[76:77]
	v_pk_mul_f32 v[110:111], v[106:107], s[76:77]
	v_pk_mul_f32 v[114:115], v[102:103], s[76:77]
	v_pk_mul_f32 v[108:109], v[104:105], v[108:109]
	v_pk_mul_f32 v[112:113], v[100:101], v[112:113]
	v_pk_mul_f32 v[110:111], v[106:107], v[110:111]
	v_pk_mul_f32 v[114:115], v[102:103], v[114:115]
	v_pk_fma_f32 v[108:109], v[104:105], v[108:109], v[104:105]
	v_pk_fma_f32 v[112:113], v[100:101], v[112:113], v[100:101]
	v_pk_fma_f32 v[110:111], v[106:107], v[110:111], v[106:107]
	v_pk_fma_f32 v[114:115], v[102:103], v[114:115], v[102:103]
	v_pk_mul_f32 v[108:109], v[108:109], s[78:79]
	v_pk_mul_f32 v[112:113], v[112:113], s[78:79]
	v_pk_mul_f32 v[110:111], v[110:111], s[78:79]
	v_pk_mul_f32 v[114:115], v[114:115], s[78:79]
	v_pk_mul_f32 v[108:109], v[108:109], s[80:81]
	v_pk_mul_f32 v[112:113], v[112:113], s[80:81]
	v_pk_mul_f32 v[110:111], v[110:111], s[80:81]
	v_pk_mul_f32 v[114:115], v[114:115], s[80:81]
	v_exp_f32_e32 v108, v108
	v_exp_f32_e32 v109, v109
	v_exp_f32_e32 v112, v112
	v_exp_f32_e32 v113, v113
	v_exp_f32_e32 v110, v110
	v_exp_f32_e32 v111, v111
	v_exp_f32_e32 v114, v114
	v_exp_f32_e32 v115, v115
	s_nop 0
	v_pk_add_f32 v[108:109], v[108:109], s[82:83]
	v_pk_add_f32 v[112:113], v[112:113], s[82:83]
	v_pk_add_f32 v[110:111], v[110:111], s[82:83]
	v_pk_add_f32 v[114:115], v[114:115], s[82:83]
	v_rcp_f32_e32 v108, v108
	v_rcp_f32_e32 v109, v109
	v_rcp_f32_e32 v112, v112
	v_rcp_f32_e32 v113, v113
	v_rcp_f32_e32 v110, v110
	v_rcp_f32_e32 v111, v111
	v_rcp_f32_e32 v114, v114
	v_rcp_f32_e32 v115, v115
	s_nop 0
	v_pk_mul_f32 v[108:109], v[104:105], v[108:109]
	v_pk_mul_f32 v[112:113], v[100:101], v[112:113]
	v_pk_mul_f32 v[110:111], v[106:107], v[110:111]
	v_pk_mul_f32 v[114:115], v[102:103], v[114:115]

.LBB0_138:
	s_andn2_b64 vcc, exec, s[4:5]
	s_cbranch_vccnz .LBB0_140
	s_mov_b32 s76, 0x3d372713
	s_mov_b32 s77, 0x3d372713
	s_mov_b32 s78, 0x3f4c422a
	s_mov_b32 s79, 0x3f4c422a
	s_mov_b32 s80, 0xc038aa3b
	s_mov_b32 s81, 0xc038aa3b
	s_mov_b32 s82, 1.0
	s_mov_b32 s83, 1.0
	v_pk_mul_f32 v[100:101], v[92:93], s[76:77]
	v_pk_mul_f32 v[104:105], v[88:89], s[76:77]
	v_pk_mul_f32 v[102:103], v[94:95], s[76:77]
	v_pk_mul_f32 v[106:107], v[90:91], s[76:77]
	v_pk_mul_f32 v[100:101], v[92:93], v[100:101]
	v_pk_mul_f32 v[104:105], v[88:89], v[104:105]
	v_pk_mul_f32 v[102:103], v[94:95], v[102:103]
	v_pk_mul_f32 v[106:107], v[90:91], v[106:107]
	v_pk_fma_f32 v[100:101], v[92:93], v[100:101], v[92:93]
	v_pk_fma_f32 v[104:105], v[88:89], v[104:105], v[88:89]
	v_pk_fma_f32 v[102:103], v[94:95], v[102:103], v[94:95]
	v_pk_fma_f32 v[106:107], v[90:91], v[106:107], v[90:91]
	v_pk_mul_f32 v[100:101], v[100:101], s[78:79]
	v_pk_mul_f32 v[104:105], v[104:105], s[78:79]
	v_pk_mul_f32 v[102:103], v[102:103], s[78:79]
	v_pk_mul_f32 v[106:107], v[106:107], s[78:79]
	v_pk_mul_f32 v[100:101], v[100:101], s[80:81]
	v_pk_mul_f32 v[104:105], v[104:105], s[80:81]
	v_pk_mul_f32 v[102:103], v[102:103], s[80:81]
	v_pk_mul_f32 v[106:107], v[106:107], s[80:81]
	v_exp_f32_e32 v100, v100
	v_exp_f32_e32 v101, v101
	v_exp_f32_e32 v104, v104
	v_exp_f32_e32 v105, v105
	v_exp_f32_e32 v102, v102
	v_exp_f32_e32 v103, v103
	v_exp_f32_e32 v106, v106
	v_exp_f32_e32 v107, v107
	s_nop 0
	v_pk_add_f32 v[100:101], v[100:101], s[82:83]
	v_pk_add_f32 v[104:105], v[104:105], s[82:83]
	v_pk_add_f32 v[102:103], v[102:103], s[82:83]
	v_pk_add_f32 v[106:107], v[106:107], s[82:83]
	v_rcp_f32_e32 v100, v100
	v_rcp_f32_e32 v101, v101
	v_rcp_f32_e32 v104, v104
	v_rcp_f32_e32 v105, v105
	v_rcp_f32_e32 v102, v102
	v_rcp_f32_e32 v103, v103
	v_rcp_f32_e32 v106, v106
	v_rcp_f32_e32 v107, v107
	s_nop 0
	v_pk_mul_f32 v[100:101], v[92:93], v[100:101]
	v_pk_mul_f32 v[104:105], v[88:89], v[104:105]
	v_pk_mul_f32 v[102:103], v[94:95], v[102:103]
	v_pk_mul_f32 v[106:107], v[90:91], v[106:107]

.LBB0_144:
	s_andn2_b64 vcc, exec, s[4:5]
	s_cbranch_vccnz .LBB0_146
	s_mov_b32 s76, 0x3d372713
	s_mov_b32 s77, 0x3d372713
	s_mov_b32 s78, 0x3f4c422a
	s_mov_b32 s79, 0x3f4c422a
	s_mov_b32 s80, 0xc038aa3b
	s_mov_b32 s81, 0xc038aa3b
	s_mov_b32 s82, 1.0
	s_mov_b32 s83, 1.0
	v_pk_mul_f32 v[88:89], v[84:85], s[76:77]
	v_pk_mul_f32 v[92:93], v[80:81], s[76:77]
	v_pk_mul_f32 v[90:91], v[86:87], s[76:77]
	v_pk_mul_f32 v[94:95], v[82:83], s[76:77]
	v_pk_mul_f32 v[88:89], v[84:85], v[88:89]
	v_pk_mul_f32 v[92:93], v[80:81], v[92:93]
	v_pk_mul_f32 v[90:91], v[86:87], v[90:91]
	v_pk_mul_f32 v[94:95], v[82:83], v[94:95]
	v_pk_fma_f32 v[88:89], v[84:85], v[88:89], v[84:85]
	v_pk_fma_f32 v[92:93], v[80:81], v[92:93], v[80:81]
	v_pk_fma_f32 v[90:91], v[86:87], v[90:91], v[86:87]
	v_pk_fma_f32 v[94:95], v[82:83], v[94:95], v[82:83]
	v_pk_mul_f32 v[88:89], v[88:89], s[78:79]
	v_pk_mul_f32 v[92:93], v[92:93], s[78:79]
	v_pk_mul_f32 v[90:91], v[90:91], s[78:79]
	v_pk_mul_f32 v[94:95], v[94:95], s[78:79]
	v_pk_mul_f32 v[88:89], v[88:89], s[80:81]
	v_pk_mul_f32 v[92:93], v[92:93], s[80:81]
	v_pk_mul_f32 v[90:91], v[90:91], s[80:81]
	v_pk_mul_f32 v[94:95], v[94:95], s[80:81]
	v_exp_f32_e32 v88, v88
	v_exp_f32_e32 v89, v89
	v_exp_f32_e32 v92, v92
	v_exp_f32_e32 v93, v93
	v_exp_f32_e32 v90, v90
	v_exp_f32_e32 v91, v91
	v_exp_f32_e32 v94, v94
	v_exp_f32_e32 v95, v95
	s_nop 0
	v_pk_add_f32 v[88:89], v[88:89], s[82:83]
	v_pk_add_f32 v[92:93], v[92:93], s[82:83]
	v_pk_add_f32 v[90:91], v[90:91], s[82:83]
	v_pk_add_f32 v[94:95], v[94:95], s[82:83]
	v_rcp_f32_e32 v88, v88
	v_rcp_f32_e32 v89, v89
	v_rcp_f32_e32 v92, v92
	v_rcp_f32_e32 v93, v93
	v_rcp_f32_e32 v90, v90
	v_rcp_f32_e32 v91, v91
	v_rcp_f32_e32 v94, v94
	v_rcp_f32_e32 v95, v95
	s_nop 0
	v_pk_mul_f32 v[88:89], v[84:85], v[88:89]
	v_pk_mul_f32 v[92:93], v[80:81], v[92:93]
	v_pk_mul_f32 v[90:91], v[86:87], v[90:91]
	v_pk_mul_f32 v[94:95], v[82:83], v[94:95]

.LBB0_150:
	s_andn2_b64 vcc, exec, s[4:5]
	s_cbranch_vccnz .LBB0_152
	s_mov_b32 s76, 0x3d372713
	s_mov_b32 s77, 0x3d372713
	s_mov_b32 s78, 0x3f4c422a
	s_mov_b32 s79, 0x3f4c422a
	s_mov_b32 s80, 0xc038aa3b
	s_mov_b32 s81, 0xc038aa3b
	s_mov_b32 s82, 1.0
	s_mov_b32 s83, 1.0
	v_pk_mul_f32 v[80:81], v[72:73], s[76:77]
	v_pk_mul_f32 v[84:85], v[68:69], s[76:77]
	v_pk_mul_f32 v[82:83], v[74:75], s[76:77]
	v_pk_mul_f32 v[86:87], v[70:71], s[76:77]
	v_pk_mul_f32 v[80:81], v[72:73], v[80:81]
	v_pk_mul_f32 v[84:85], v[68:69], v[84:85]
	v_pk_mul_f32 v[82:83], v[74:75], v[82:83]
	v_pk_mul_f32 v[86:87], v[70:71], v[86:87]
	v_pk_fma_f32 v[80:81], v[72:73], v[80:81], v[72:73]
	v_pk_fma_f32 v[84:85], v[68:69], v[84:85], v[68:69]
	v_pk_fma_f32 v[82:83], v[74:75], v[82:83], v[74:75]
	v_pk_fma_f32 v[86:87], v[70:71], v[86:87], v[70:71]
	v_pk_mul_f32 v[80:81], v[80:81], s[78:79]
	v_pk_mul_f32 v[84:85], v[84:85], s[78:79]
	v_pk_mul_f32 v[82:83], v[82:83], s[78:79]
	v_pk_mul_f32 v[86:87], v[86:87], s[78:79]
	v_pk_mul_f32 v[80:81], v[80:81], s[80:81]
	v_pk_mul_f32 v[84:85], v[84:85], s[80:81]
	v_pk_mul_f32 v[82:83], v[82:83], s[80:81]
	v_pk_mul_f32 v[86:87], v[86:87], s[80:81]
	v_exp_f32_e32 v80, v80
	v_exp_f32_e32 v81, v81
	v_exp_f32_e32 v84, v84
	v_exp_f32_e32 v85, v85
	v_exp_f32_e32 v82, v82
	v_exp_f32_e32 v83, v83
	v_exp_f32_e32 v86, v86
	v_exp_f32_e32 v87, v87
	s_nop 0
	v_pk_add_f32 v[80:81], v[80:81], s[82:83]
	v_pk_add_f32 v[84:85], v[84:85], s[82:83]
	v_pk_add_f32 v[82:83], v[82:83], s[82:83]
	v_pk_add_f32 v[86:87], v[86:87], s[82:83]
	v_rcp_f32_e32 v80, v80
	v_rcp_f32_e32 v81, v81
	v_rcp_f32_e32 v84, v84
	v_rcp_f32_e32 v85, v85
	v_rcp_f32_e32 v82, v82
	v_rcp_f32_e32 v83, v83
	v_rcp_f32_e32 v86, v86
	v_rcp_f32_e32 v87, v87
	s_nop 0
	v_pk_mul_f32 v[80:81], v[72:73], v[80:81]
	v_pk_mul_f32 v[84:85], v[68:69], v[84:85]
	v_pk_mul_f32 v[82:83], v[74:75], v[82:83]
	v_pk_mul_f32 v[86:87], v[70:71], v[86:87]

.LBB0_156:
	s_andn2_b64 vcc, exec, s[4:5]
	s_cbranch_vccnz .LBB0_158
	s_mov_b32 s76, 0x3d372713
	s_mov_b32 s77, 0x3d372713
	s_mov_b32 s78, 0x3f4c422a
	s_mov_b32 s79, 0x3f4c422a
	s_mov_b32 s80, 0xc038aa3b
	s_mov_b32 s81, 0xc038aa3b
	s_mov_b32 s82, 1.0
	s_mov_b32 s83, 1.0
	v_pk_mul_f32 v[68:69], v[60:61], s[76:77]
	v_pk_mul_f32 v[72:73], v[56:57], s[76:77]
	v_pk_mul_f32 v[70:71], v[62:63], s[76:77]
	v_pk_mul_f32 v[74:75], v[58:59], s[76:77]
	v_pk_mul_f32 v[68:69], v[60:61], v[68:69]
	v_pk_mul_f32 v[72:73], v[56:57], v[72:73]
	v_pk_mul_f32 v[70:71], v[62:63], v[70:71]
	v_pk_mul_f32 v[74:75], v[58:59], v[74:75]
	v_pk_fma_f32 v[68:69], v[60:61], v[68:69], v[60:61]
	v_pk_fma_f32 v[72:73], v[56:57], v[72:73], v[56:57]
	v_pk_fma_f32 v[70:71], v[62:63], v[70:71], v[62:63]
	v_pk_fma_f32 v[74:75], v[58:59], v[74:75], v[58:59]
	v_pk_mul_f32 v[68:69], v[68:69], s[78:79]
	v_pk_mul_f32 v[72:73], v[72:73], s[78:79]
	v_pk_mul_f32 v[70:71], v[70:71], s[78:79]
	v_pk_mul_f32 v[74:75], v[74:75], s[78:79]
	v_pk_mul_f32 v[68:69], v[68:69], s[80:81]
	v_pk_mul_f32 v[72:73], v[72:73], s[80:81]
	v_pk_mul_f32 v[70:71], v[70:71], s[80:81]
	v_pk_mul_f32 v[74:75], v[74:75], s[80:81]
	v_exp_f32_e32 v68, v68
	v_exp_f32_e32 v69, v69
	v_exp_f32_e32 v72, v72
	v_exp_f32_e32 v73, v73
	v_exp_f32_e32 v70, v70
	v_exp_f32_e32 v71, v71
	v_exp_f32_e32 v74, v74
	v_exp_f32_e32 v75, v75
	s_nop 0
	v_pk_add_f32 v[68:69], v[68:69], s[82:83]
	v_pk_add_f32 v[72:73], v[72:73], s[82:83]
	v_pk_add_f32 v[70:71], v[70:71], s[82:83]
	v_pk_add_f32 v[74:75], v[74:75], s[82:83]
	v_rcp_f32_e32 v68, v68
	v_rcp_f32_e32 v69, v69
	v_rcp_f32_e32 v72, v72
	v_rcp_f32_e32 v73, v73
	v_rcp_f32_e32 v70, v70
	v_rcp_f32_e32 v71, v71
	v_rcp_f32_e32 v74, v74
	v_rcp_f32_e32 v75, v75
	s_nop 0
	v_pk_mul_f32 v[68:69], v[60:61], v[68:69]
	v_pk_mul_f32 v[72:73], v[56:57], v[72:73]
	v_pk_mul_f32 v[70:71], v[62:63], v[70:71]
	v_pk_mul_f32 v[74:75], v[58:59], v[74:75]

.LBB0_162:
	s_andn2_b64 vcc, exec, s[4:5]
	s_cbranch_vccnz .LBB0_164
	s_mov_b32 s76, 0x3d372713
	s_mov_b32 s77, 0x3d372713
	s_mov_b32 s78, 0x3f4c422a
	s_mov_b32 s79, 0x3f4c422a
	s_mov_b32 s80, 0xc038aa3b
	s_mov_b32 s81, 0xc038aa3b
	s_mov_b32 s82, 1.0
	s_mov_b32 s83, 1.0
	v_pk_mul_f32 v[56:57], v[52:53], s[76:77]
	v_pk_mul_f32 v[60:61], v[48:49], s[76:77]
	v_pk_mul_f32 v[58:59], v[54:55], s[76:77]
	v_pk_mul_f32 v[62:63], v[50:51], s[76:77]
	v_pk_mul_f32 v[56:57], v[52:53], v[56:57]
	v_pk_mul_f32 v[60:61], v[48:49], v[60:61]
	v_pk_mul_f32 v[58:59], v[54:55], v[58:59]
	v_pk_mul_f32 v[62:63], v[50:51], v[62:63]
	v_pk_fma_f32 v[56:57], v[52:53], v[56:57], v[52:53]
	v_pk_fma_f32 v[60:61], v[48:49], v[60:61], v[48:49]
	v_pk_fma_f32 v[58:59], v[54:55], v[58:59], v[54:55]
	v_pk_fma_f32 v[62:63], v[50:51], v[62:63], v[50:51]
	v_pk_mul_f32 v[56:57], v[56:57], s[78:79]
	v_pk_mul_f32 v[60:61], v[60:61], s[78:79]
	v_pk_mul_f32 v[58:59], v[58:59], s[78:79]
	v_pk_mul_f32 v[62:63], v[62:63], s[78:79]
	v_pk_mul_f32 v[56:57], v[56:57], s[80:81]
	v_pk_mul_f32 v[60:61], v[60:61], s[80:81]
	v_pk_mul_f32 v[58:59], v[58:59], s[80:81]
	v_pk_mul_f32 v[62:63], v[62:63], s[80:81]
	v_exp_f32_e32 v56, v56
	v_exp_f32_e32 v57, v57
	v_exp_f32_e32 v60, v60
	v_exp_f32_e32 v61, v61
	v_exp_f32_e32 v58, v58
	v_exp_f32_e32 v59, v59
	v_exp_f32_e32 v62, v62
	v_exp_f32_e32 v63, v63
	s_nop 0
	v_pk_add_f32 v[56:57], v[56:57], s[82:83]
	v_pk_add_f32 v[60:61], v[60:61], s[82:83]
	v_pk_add_f32 v[58:59], v[58:59], s[82:83]
	v_pk_add_f32 v[62:63], v[62:63], s[82:83]
	v_rcp_f32_e32 v56, v56
	v_rcp_f32_e32 v57, v57
	v_rcp_f32_e32 v60, v60
	v_rcp_f32_e32 v61, v61
	v_rcp_f32_e32 v58, v58
	v_rcp_f32_e32 v59, v59
	v_rcp_f32_e32 v62, v62
	v_rcp_f32_e32 v63, v63
	s_nop 0
	v_pk_mul_f32 v[56:57], v[52:53], v[56:57]
	v_pk_mul_f32 v[60:61], v[48:49], v[60:61]
	v_pk_mul_f32 v[58:59], v[54:55], v[58:59]
	v_pk_mul_f32 v[62:63], v[50:51], v[62:63]

.LBB0_168:
	s_andn2_b64 vcc, exec, s[4:5]
	s_cbranch_vccnz .LBB0_170
	s_mov_b32 s76, 0x3d372713
	s_mov_b32 s77, 0x3d372713
	s_mov_b32 s78, 0x3f4c422a
	s_mov_b32 s79, 0x3f4c422a
	s_mov_b32 s80, 0xc038aa3b
	s_mov_b32 s81, 0xc038aa3b
	s_mov_b32 s82, 1.0
	s_mov_b32 s83, 1.0
	v_pk_mul_f32 v[48:49], v[40:41], s[76:77]
	v_pk_mul_f32 v[52:53], v[36:37], s[76:77]
	v_pk_mul_f32 v[50:51], v[42:43], s[76:77]
	v_pk_mul_f32 v[54:55], v[38:39], s[76:77]
	v_pk_mul_f32 v[48:49], v[40:41], v[48:49]
	v_pk_mul_f32 v[52:53], v[36:37], v[52:53]
	v_pk_mul_f32 v[50:51], v[42:43], v[50:51]
	v_pk_mul_f32 v[54:55], v[38:39], v[54:55]
	v_pk_fma_f32 v[48:49], v[40:41], v[48:49], v[40:41]
	v_pk_fma_f32 v[52:53], v[36:37], v[52:53], v[36:37]
	v_pk_fma_f32 v[50:51], v[42:43], v[50:51], v[42:43]
	v_pk_fma_f32 v[54:55], v[38:39], v[54:55], v[38:39]
	v_pk_mul_f32 v[48:49], v[48:49], s[78:79]
	v_pk_mul_f32 v[52:53], v[52:53], s[78:79]
	v_pk_mul_f32 v[50:51], v[50:51], s[78:79]
	v_pk_mul_f32 v[54:55], v[54:55], s[78:79]
	v_pk_mul_f32 v[48:49], v[48:49], s[80:81]
	v_pk_mul_f32 v[52:53], v[52:53], s[80:81]
	v_pk_mul_f32 v[50:51], v[50:51], s[80:81]
	v_pk_mul_f32 v[54:55], v[54:55], s[80:81]
	v_exp_f32_e32 v48, v48
	v_exp_f32_e32 v49, v49
	v_exp_f32_e32 v52, v52
	v_exp_f32_e32 v53, v53
	v_exp_f32_e32 v50, v50
	v_exp_f32_e32 v51, v51
	v_exp_f32_e32 v54, v54
	v_exp_f32_e32 v55, v55
	s_nop 0
	v_pk_add_f32 v[48:49], v[48:49], s[82:83]
	v_pk_add_f32 v[52:53], v[52:53], s[82:83]
	v_pk_add_f32 v[50:51], v[50:51], s[82:83]
	v_pk_add_f32 v[54:55], v[54:55], s[82:83]
	v_rcp_f32_e32 v48, v48
	v_rcp_f32_e32 v49, v49
	v_rcp_f32_e32 v52, v52
	v_rcp_f32_e32 v53, v53
	v_rcp_f32_e32 v50, v50
	v_rcp_f32_e32 v51, v51
	v_rcp_f32_e32 v54, v54
	v_rcp_f32_e32 v55, v55
	s_nop 0
	v_pk_mul_f32 v[48:49], v[40:41], v[48:49]
	v_pk_mul_f32 v[52:53], v[36:37], v[52:53]
	v_pk_mul_f32 v[50:51], v[42:43], v[50:51]
	v_pk_mul_f32 v[54:55], v[38:39], v[54:55]

.LBB0_174:
	s_andn2_b64 vcc, exec, s[4:5]
	s_cbranch_vccnz .LBB0_176
	s_mov_b32 s76, 0x3d372713
	s_mov_b32 s77, 0x3d372713
	s_mov_b32 s78, 0x3f4c422a
	s_mov_b32 s79, 0x3f4c422a
	s_mov_b32 s80, 0xc038aa3b
	s_mov_b32 s81, 0xc038aa3b
	s_mov_b32 s82, 1.0
	s_mov_b32 s83, 1.0
	v_pk_mul_f32 v[36:37], v[32:33], s[76:77]
	v_pk_mul_f32 v[40:41], v[28:29], s[76:77]
	v_pk_mul_f32 v[38:39], v[34:35], s[76:77]
	v_pk_mul_f32 v[42:43], v[30:31], s[76:77]
	v_pk_mul_f32 v[36:37], v[32:33], v[36:37]
	v_pk_mul_f32 v[40:41], v[28:29], v[40:41]
	v_pk_mul_f32 v[38:39], v[34:35], v[38:39]
	v_pk_mul_f32 v[42:43], v[30:31], v[42:43]
	v_pk_fma_f32 v[36:37], v[32:33], v[36:37], v[32:33]
	v_pk_fma_f32 v[40:41], v[28:29], v[40:41], v[28:29]
	v_pk_fma_f32 v[38:39], v[34:35], v[38:39], v[34:35]
	v_pk_fma_f32 v[42:43], v[30:31], v[42:43], v[30:31]
	v_pk_mul_f32 v[36:37], v[36:37], s[78:79]
	v_pk_mul_f32 v[40:41], v[40:41], s[78:79]
	v_pk_mul_f32 v[38:39], v[38:39], s[78:79]
	v_pk_mul_f32 v[42:43], v[42:43], s[78:79]
	v_pk_mul_f32 v[36:37], v[36:37], s[80:81]
	v_pk_mul_f32 v[40:41], v[40:41], s[80:81]
	v_pk_mul_f32 v[38:39], v[38:39], s[80:81]
	v_pk_mul_f32 v[42:43], v[42:43], s[80:81]
	v_exp_f32_e32 v36, v36
	v_exp_f32_e32 v37, v37
	v_exp_f32_e32 v40, v40
	v_exp_f32_e32 v41, v41
	v_exp_f32_e32 v38, v38
	v_exp_f32_e32 v39, v39
	v_exp_f32_e32 v42, v42
	v_exp_f32_e32 v43, v43
	s_nop 0
	v_pk_add_f32 v[36:37], v[36:37], s[82:83]
	v_pk_add_f32 v[40:41], v[40:41], s[82:83]
	v_pk_add_f32 v[38:39], v[38:39], s[82:83]
	v_pk_add_f32 v[42:43], v[42:43], s[82:83]
	v_rcp_f32_e32 v36, v36
	v_rcp_f32_e32 v37, v37
	v_rcp_f32_e32 v40, v40
	v_rcp_f32_e32 v41, v41
	v_rcp_f32_e32 v38, v38
	v_rcp_f32_e32 v39, v39
	v_rcp_f32_e32 v42, v42
	v_rcp_f32_e32 v43, v43
	s_nop 0
	v_pk_mul_f32 v[36:37], v[32:33], v[36:37]
	v_pk_mul_f32 v[40:41], v[28:29], v[40:41]
	v_pk_mul_f32 v[38:39], v[34:35], v[38:39]
	v_pk_mul_f32 v[42:43], v[30:31], v[42:43]

.LBB0_180:
	s_andn2_b64 vcc, exec, s[4:5]
	s_cbranch_vccnz .LBB0_182
	s_mov_b32 s76, 0x3d372713
	s_mov_b32 s77, 0x3d372713
	s_mov_b32 s78, 0x3f4c422a
	s_mov_b32 s79, 0x3f4c422a
	s_mov_b32 s80, 0xc038aa3b
	s_mov_b32 s81, 0xc038aa3b
	s_mov_b32 s82, 1.0
	s_mov_b32 s83, 1.0
	v_pk_mul_f32 v[28:29], v[24:25], s[76:77]
	v_pk_mul_f32 v[32:33], v[20:21], s[76:77]
	v_pk_mul_f32 v[30:31], v[26:27], s[76:77]
	v_pk_mul_f32 v[34:35], v[22:23], s[76:77]
	v_pk_mul_f32 v[28:29], v[24:25], v[28:29]
	v_pk_mul_f32 v[32:33], v[20:21], v[32:33]
	v_pk_mul_f32 v[30:31], v[26:27], v[30:31]
	v_pk_mul_f32 v[34:35], v[22:23], v[34:35]
	v_pk_fma_f32 v[28:29], v[24:25], v[28:29], v[24:25]
	v_pk_fma_f32 v[32:33], v[20:21], v[32:33], v[20:21]
	v_pk_fma_f32 v[30:31], v[26:27], v[30:31], v[26:27]
	v_pk_fma_f32 v[34:35], v[22:23], v[34:35], v[22:23]
	v_pk_mul_f32 v[28:29], v[28:29], s[78:79]
	v_pk_mul_f32 v[32:33], v[32:33], s[78:79]
	v_pk_mul_f32 v[30:31], v[30:31], s[78:79]
	v_pk_mul_f32 v[34:35], v[34:35], s[78:79]
	v_pk_mul_f32 v[28:29], v[28:29], s[80:81]
	v_pk_mul_f32 v[32:33], v[32:33], s[80:81]
	v_pk_mul_f32 v[30:31], v[30:31], s[80:81]
	v_pk_mul_f32 v[34:35], v[34:35], s[80:81]
	v_exp_f32_e32 v28, v28
	v_exp_f32_e32 v29, v29
	v_exp_f32_e32 v32, v32
	v_exp_f32_e32 v33, v33
	v_exp_f32_e32 v30, v30
	v_exp_f32_e32 v31, v31
	v_exp_f32_e32 v34, v34
	v_exp_f32_e32 v35, v35
	s_nop 0
	v_pk_add_f32 v[28:29], v[28:29], s[82:83]
	v_pk_add_f32 v[32:33], v[32:33], s[82:83]
	v_pk_add_f32 v[30:31], v[30:31], s[82:83]
	v_pk_add_f32 v[34:35], v[34:35], s[82:83]
	v_rcp_f32_e32 v28, v28
	v_rcp_f32_e32 v29, v29
	v_rcp_f32_e32 v32, v32
	v_rcp_f32_e32 v33, v33
	v_rcp_f32_e32 v30, v30
	v_rcp_f32_e32 v31, v31
	v_rcp_f32_e32 v34, v34
	v_rcp_f32_e32 v35, v35
	s_nop 0
	v_pk_mul_f32 v[28:29], v[24:25], v[28:29]
	v_pk_mul_f32 v[32:33], v[20:21], v[32:33]
	v_pk_mul_f32 v[30:31], v[26:27], v[30:31]
	v_pk_mul_f32 v[34:35], v[22:23], v[34:35]

.LBB0_186:
	s_andn2_b64 vcc, exec, s[4:5]
	s_cbranch_vccnz .LBB0_188
	s_mov_b32 s76, 0x3d372713
	s_mov_b32 s77, 0x3d372713
	s_mov_b32 s78, 0x3f4c422a
	s_mov_b32 s79, 0x3f4c422a
	s_mov_b32 s80, 0xc038aa3b
	s_mov_b32 s81, 0xc038aa3b
	s_mov_b32 s82, 1.0
	s_mov_b32 s83, 1.0
	v_pk_mul_f32 v[20:21], v[16:17], s[76:77]
	v_pk_mul_f32 v[24:25], v[12:13], s[76:77]
	v_pk_mul_f32 v[22:23], v[18:19], s[76:77]
	v_pk_mul_f32 v[26:27], v[14:15], s[76:77]
	v_pk_mul_f32 v[20:21], v[16:17], v[20:21]
	v_pk_mul_f32 v[24:25], v[12:13], v[24:25]
	v_pk_mul_f32 v[22:23], v[18:19], v[22:23]
	v_pk_mul_f32 v[26:27], v[14:15], v[26:27]
	v_pk_fma_f32 v[20:21], v[16:17], v[20:21], v[16:17]
	v_pk_fma_f32 v[24:25], v[12:13], v[24:25], v[12:13]
	v_pk_fma_f32 v[22:23], v[18:19], v[22:23], v[18:19]
	v_pk_fma_f32 v[26:27], v[14:15], v[26:27], v[14:15]
	v_pk_mul_f32 v[20:21], v[20:21], s[78:79]
	v_pk_mul_f32 v[24:25], v[24:25], s[78:79]
	v_pk_mul_f32 v[22:23], v[22:23], s[78:79]
	v_pk_mul_f32 v[26:27], v[26:27], s[78:79]
	v_pk_mul_f32 v[20:21], v[20:21], s[80:81]
	v_pk_mul_f32 v[24:25], v[24:25], s[80:81]
	v_pk_mul_f32 v[22:23], v[22:23], s[80:81]
	v_pk_mul_f32 v[26:27], v[26:27], s[80:81]
	v_exp_f32_e32 v20, v20
	v_exp_f32_e32 v21, v21
	v_exp_f32_e32 v24, v24
	v_exp_f32_e32 v25, v25
	v_exp_f32_e32 v22, v22
	v_exp_f32_e32 v23, v23
	v_exp_f32_e32 v26, v26
	v_exp_f32_e32 v27, v27
	s_nop 0
	v_pk_add_f32 v[20:21], v[20:21], s[82:83]
	v_pk_add_f32 v[24:25], v[24:25], s[82:83]
	v_pk_add_f32 v[22:23], v[22:23], s[82:83]
	v_pk_add_f32 v[26:27], v[26:27], s[82:83]
	v_rcp_f32_e32 v20, v20
	v_rcp_f32_e32 v21, v21
	v_rcp_f32_e32 v24, v24
	v_rcp_f32_e32 v25, v25
	v_rcp_f32_e32 v22, v22
	v_rcp_f32_e32 v23, v23
	v_rcp_f32_e32 v26, v26
	v_rcp_f32_e32 v27, v27
	s_nop 0
	v_pk_mul_f32 v[20:21], v[16:17], v[20:21]
	v_pk_mul_f32 v[24:25], v[12:13], v[24:25]
	v_pk_mul_f32 v[22:23], v[18:19], v[22:23]
	v_pk_mul_f32 v[26:27], v[14:15], v[26:27]

.LBB0_192:
	s_andn2_b64 vcc, exec, s[4:5]
	s_cbranch_vccnz .LBB0_194
	s_mov_b32 s76, 0x3d372713
	s_mov_b32 s77, 0x3d372713
	s_mov_b32 s78, 0x3f4c422a
	s_mov_b32 s79, 0x3f4c422a
	s_mov_b32 s80, 0xc038aa3b
	s_mov_b32 s81, 0xc038aa3b
	s_mov_b32 s82, 1.0
	s_mov_b32 s83, 1.0
	v_pk_mul_f32 v[12:13], v[8:9], s[76:77]
	v_pk_mul_f32 v[16:17], v[4:5], s[76:77]
	v_pk_mul_f32 v[14:15], v[10:11], s[76:77]
	v_pk_mul_f32 v[18:19], v[6:7], s[76:77]
	v_pk_mul_f32 v[12:13], v[8:9], v[12:13]
	v_pk_mul_f32 v[16:17], v[4:5], v[16:17]
	v_pk_mul_f32 v[14:15], v[10:11], v[14:15]
	v_pk_mul_f32 v[18:19], v[6:7], v[18:19]
	v_pk_fma_f32 v[12:13], v[8:9], v[12:13], v[8:9]
	v_pk_fma_f32 v[16:17], v[4:5], v[16:17], v[4:5]
	v_pk_fma_f32 v[14:15], v[10:11], v[14:15], v[10:11]
	v_pk_fma_f32 v[18:19], v[6:7], v[18:19], v[6:7]
	v_pk_mul_f32 v[12:13], v[12:13], s[78:79]
	v_pk_mul_f32 v[16:17], v[16:17], s[78:79]
	v_pk_mul_f32 v[14:15], v[14:15], s[78:79]
	v_pk_mul_f32 v[18:19], v[18:19], s[78:79]
	v_pk_mul_f32 v[12:13], v[12:13], s[80:81]
	v_pk_mul_f32 v[16:17], v[16:17], s[80:81]
	v_pk_mul_f32 v[14:15], v[14:15], s[80:81]
	v_pk_mul_f32 v[18:19], v[18:19], s[80:81]
	v_exp_f32_e32 v12, v12
	v_exp_f32_e32 v13, v13
	v_exp_f32_e32 v16, v16
	v_exp_f32_e32 v17, v17
	v_exp_f32_e32 v14, v14
	v_exp_f32_e32 v15, v15
	v_exp_f32_e32 v18, v18
	v_exp_f32_e32 v19, v19
	s_nop 0
	v_pk_add_f32 v[12:13], v[12:13], s[82:83]
	v_pk_add_f32 v[16:17], v[16:17], s[82:83]
	v_pk_add_f32 v[14:15], v[14:15], s[82:83]
	v_pk_add_f32 v[18:19], v[18:19], s[82:83]
	v_rcp_f32_e32 v12, v12
	v_rcp_f32_e32 v13, v13
	v_rcp_f32_e32 v16, v16
	v_rcp_f32_e32 v17, v17
	v_rcp_f32_e32 v14, v14
	v_rcp_f32_e32 v15, v15
	v_rcp_f32_e32 v18, v18
	v_rcp_f32_e32 v19, v19
	s_nop 0
	v_pk_mul_f32 v[12:13], v[8:9], v[12:13]
	v_pk_mul_f32 v[16:17], v[4:5], v[16:17]
	v_pk_mul_f32 v[14:15], v[10:11], v[14:15]
	v_pk_mul_f32 v[18:19], v[6:7], v[18:19]
